# last-layer branch epilogue by hand: 14 of the 16 gate loads in flight instead of one at a time behind vmcnt(0)
# speedup vs baseline: 1.0203x; 1.0016x over previous
; DEV float bflo(unsigned w) { return __uint_as_float(w << 16); }
; DEV float bfhi(unsigned w) { return __uint_as_float(w & 0xffff0000u); }
; template <int WT>
; DEV void branch_item(const Params& p, int l, int t0, int tf, char* smem, int tid) {
;     ...
;   for (int br = 0; br < 3; ++br) {
;     f32x4 acc[2][WT];
;     zero_acc<2, WT>(acc);
;     constexpr bool PREG = (WT <= 6);
;     uint2 gzr[2][PREG ? WT : 1];
;     if (PREG) {
; #pragma unroll
;       for (int n = 0; n < 2; ++n)
; #pragma unroll
;         for (int t = 0; t < (PREG ? WT : 1); ++t)
;           gzr[n][t] = *(const uint2*)(p.z + (long)(t0 + wt * (WT * 16) + t * 16 + fr) * NINP + C_BRG + br * 1024 + f0 + wn * 32 + n * 16 + fq * 4);
;     }
;     gemm_mainloop<2, WT>(p.WbrT + ((long)(l * 3 + br) * 1024 + f0) * 512, 512, p.Y + ((long)br * TG + t0) * 512, 512, 512, smem, tid, acc);
; #pragma unroll
;     for (int n = 0; n < 2; ++n) {
; #pragma unroll
;       for (int t = 0; t < WT; ++t) {
;         const uint2 gz = PREG ? gzr[n][PREG ? t : 0]
;                               : *(const uint2*)(p.z + (long)(t0 + wt * (WT * 16) + t * 16 + fr) * NINP + C_BRG + br * 1024 + f0 + wn * 32 + n * 16 + fq * 4);
;         mg[n][t][0] += bflo(gz.x) * acc[n][t][0];
;         mg[n][t][1] += bfhi(gz.x) * acc[n][t][1];
;         mg[n][t][2] += bflo(gz.y) * acc[n][t][2];
;         mg[n][t][3] += bfhi(gz.y) * acc[n][t][3];
;       }
;     }
.LBB0_1199:
	s_lshl_b32 s24, s7, 11
	s_add_i32 s7, s7, 1
	v_lshl_add_u64 v[136:137], v[136:137], 0, s[96:97]
	v_lshl_add_u64 v[142:143], v[142:143], 0, s[96:97]
	v_lshl_add_u64 v[144:145], v[144:145], 0, s[96:97]
	v_lshl_add_u64 v[150:151], v[150:151], 0, s[96:97]
	v_lshl_add_u64 v[152:153], v[152:153], 0, s[4:5]
	v_lshl_add_u64 v[154:155], v[154:155], 0, s[4:5]
	v_lshl_add_u64 v[232:233], v[110:111], 0, s[24:25]
	global_load_dwordx2 v[232:233], v[232:233], off
	v_lshl_add_u64 v[234:235], v[114:115], 0, s[24:25]
	global_load_dwordx2 v[234:235], v[234:235], off
	v_lshl_add_u64 v[236:237], v[116:117], 0, s[24:25]
	global_load_dwordx2 v[236:237], v[236:237], off
	v_lshl_add_u64 v[238:239], v[118:119], 0, s[24:25]
	global_load_dwordx2 v[238:239], v[238:239], off
	v_lshl_add_u64 v[240:241], v[120:121], 0, s[24:25]
	global_load_dwordx2 v[240:241], v[240:241], off
	v_lshl_add_u64 v[242:243], v[126:127], 0, s[24:25]
	global_load_dwordx2 v[242:243], v[242:243], off
	v_lshl_add_u64 v[244:245], v[128:129], 0, s[24:25]
	global_load_dwordx2 v[244:245], v[244:245], off
	v_lshl_add_u64 v[246:247], v[130:131], 0, s[24:25]
	global_load_dwordx2 v[246:247], v[246:247], off
	v_lshl_add_u64 v[248:249], v[110:111], 0, s[24:25]
	global_load_dwordx2 v[248:249], v[248:249], off offset:32
	v_lshl_add_u64 v[250:251], v[114:115], 0, s[24:25]
	global_load_dwordx2 v[250:251], v[250:251], off offset:32
	v_lshl_add_u64 v[186:187], v[116:117], 0, s[24:25]
	global_load_dwordx2 v[186:187], v[186:187], off offset:32
	v_lshl_add_u64 v[188:189], v[118:119], 0, s[24:25]
	global_load_dwordx2 v[188:189], v[188:189], off offset:32
	v_lshl_add_u64 v[190:191], v[120:121], 0, s[24:25]
	global_load_dwordx2 v[190:191], v[190:191], off offset:32
	v_lshl_add_u64 v[192:193], v[126:127], 0, s[24:25]
	global_load_dwordx2 v[192:193], v[192:193], off offset:32
	s_waitcnt vmcnt(13)
	v_mov_b32_e32 v194, v233
	v_and_b32_e32 v233, 0xffff0000, v232
	v_lshlrev_b32_e32 v232, 16, v232
	v_pk_fma_f32 v[182:183], v[60:61], v[232:233], v[182:183]
	v_lshlrev_b32_e32 v232, 16, v194
	v_and_b32_e32 v233, 0xffff0000, v194
	v_pk_fma_f32 v[184:185], v[62:63], v[232:233], v[184:185]
	v_lshl_add_u64 v[60:61], v[128:129], 0, s[24:25]
	global_load_dwordx2 v[60:61], v[60:61], off offset:32
	s_waitcnt vmcnt(13)
	v_mov_b32_e32 v194, v235
	v_and_b32_e32 v235, 0xffff0000, v234
	v_lshlrev_b32_e32 v234, 16, v234
	v_pk_fma_f32 v[178:179], v[56:57], v[234:235], v[178:179]
	v_lshlrev_b32_e32 v234, 16, v194
	v_and_b32_e32 v235, 0xffff0000, v194
	v_pk_fma_f32 v[180:181], v[58:59], v[234:235], v[180:181]
	v_lshl_add_u64 v[56:57], v[130:131], 0, s[24:25]
	global_load_dwordx2 v[56:57], v[56:57], off offset:32
	s_waitcnt vmcnt(13)
	v_mov_b32_e32 v194, v237
	v_and_b32_e32 v237, 0xffff0000, v236
	v_lshlrev_b32_e32 v236, 16, v236
	v_pk_fma_f32 v[174:175], v[52:53], v[236:237], v[174:175]
	v_lshlrev_b32_e32 v236, 16, v194
	v_and_b32_e32 v237, 0xffff0000, v194
	v_pk_fma_f32 v[176:177], v[54:55], v[236:237], v[176:177]
	s_waitcnt vmcnt(12)
	v_mov_b32_e32 v194, v239
	v_and_b32_e32 v239, 0xffff0000, v238
	v_lshlrev_b32_e32 v238, 16, v238
	v_pk_fma_f32 v[170:171], v[48:49], v[238:239], v[170:171]
	v_lshlrev_b32_e32 v238, 16, v194
	v_and_b32_e32 v239, 0xffff0000, v194
	v_pk_fma_f32 v[172:173], v[50:51], v[238:239], v[172:173]
	s_waitcnt vmcnt(11)
	v_mov_b32_e32 v194, v241
	v_and_b32_e32 v241, 0xffff0000, v240
	v_lshlrev_b32_e32 v240, 16, v240
	v_pk_fma_f32 v[166:167], v[44:45], v[240:241], v[166:167]
	v_lshlrev_b32_e32 v240, 16, v194
	v_and_b32_e32 v241, 0xffff0000, v194
	v_pk_fma_f32 v[168:169], v[46:47], v[240:241], v[168:169]
	s_waitcnt vmcnt(10)
	v_mov_b32_e32 v194, v243
	v_and_b32_e32 v243, 0xffff0000, v242
	v_lshlrev_b32_e32 v242, 16, v242
	v_pk_fma_f32 v[158:159], v[40:41], v[242:243], v[158:159]
	v_lshlrev_b32_e32 v242, 16, v194
	v_and_b32_e32 v243, 0xffff0000, v194
	v_pk_fma_f32 v[160:161], v[42:43], v[242:243], v[160:161]
	s_waitcnt vmcnt(9)
	v_mov_b32_e32 v194, v245
	v_and_b32_e32 v245, 0xffff0000, v244
	v_lshlrev_b32_e32 v244, 16, v244
	v_pk_fma_f32 v[146:147], v[36:37], v[244:245], v[146:147]
	v_lshlrev_b32_e32 v244, 16, v194
	v_and_b32_e32 v245, 0xffff0000, v194
	v_pk_fma_f32 v[148:149], v[38:39], v[244:245], v[148:149]
	s_waitcnt vmcnt(8)
	v_mov_b32_e32 v194, v247
	v_and_b32_e32 v247, 0xffff0000, v246
	v_lshlrev_b32_e32 v246, 16, v246
	v_pk_fma_f32 v[138:139], v[32:33], v[246:247], v[138:139]
	v_lshlrev_b32_e32 v246, 16, v194
	v_and_b32_e32 v247, 0xffff0000, v194
	v_pk_fma_f32 v[140:141], v[34:35], v[246:247], v[140:141]
	s_waitcnt vmcnt(7)
	v_mov_b32_e32 v194, v249
	v_and_b32_e32 v249, 0xffff0000, v248
	v_lshlrev_b32_e32 v248, 16, v248
	v_pk_fma_f32 v[132:133], v[28:29], v[248:249], v[132:133]
	v_lshlrev_b32_e32 v248, 16, v194
	v_and_b32_e32 v249, 0xffff0000, v194
	v_pk_fma_f32 v[134:135], v[30:31], v[248:249], v[134:135]
	s_waitcnt vmcnt(6)
	v_mov_b32_e32 v194, v251
	v_and_b32_e32 v251, 0xffff0000, v250
	v_lshlrev_b32_e32 v250, 16, v250
	v_pk_fma_f32 v[122:123], v[24:25], v[250:251], v[122:123]
	v_lshlrev_b32_e32 v250, 16, v194
	v_and_b32_e32 v251, 0xffff0000, v194
	v_pk_fma_f32 v[124:125], v[26:27], v[250:251], v[124:125]
	s_waitcnt vmcnt(5)
	v_mov_b32_e32 v194, v187
	v_and_b32_e32 v187, 0xffff0000, v186
	v_lshlrev_b32_e32 v186, 16, v186
	v_pk_fma_f32 v[108:109], v[20:21], v[186:187], v[108:109]
	v_lshlrev_b32_e32 v186, 16, v194
	v_and_b32_e32 v187, 0xffff0000, v194
	v_pk_fma_f32 v[112:113], v[22:23], v[186:187], v[112:113]
	s_waitcnt vmcnt(4)
	v_mov_b32_e32 v194, v189
	v_and_b32_e32 v189, 0xffff0000, v188
	v_lshlrev_b32_e32 v188, 16, v188
	v_pk_fma_f32 v[100:101], v[16:17], v[188:189], v[100:101]
	v_lshlrev_b32_e32 v188, 16, v194
	v_and_b32_e32 v189, 0xffff0000, v194
	v_pk_fma_f32 v[102:103], v[18:19], v[188:189], v[102:103]
	s_waitcnt vmcnt(3)
	v_mov_b32_e32 v194, v191
	v_and_b32_e32 v191, 0xffff0000, v190
	v_lshlrev_b32_e32 v190, 16, v190
	v_pk_fma_f32 v[96:97], v[12:13], v[190:191], v[96:97]
	v_lshlrev_b32_e32 v190, 16, v194
	v_and_b32_e32 v191, 0xffff0000, v194
	v_pk_fma_f32 v[98:99], v[14:15], v[190:191], v[98:99]
	s_waitcnt vmcnt(2)
	v_mov_b32_e32 v194, v193
	v_and_b32_e32 v193, 0xffff0000, v192
	v_lshlrev_b32_e32 v192, 16, v192
	v_pk_fma_f32 v[92:93], v[8:9], v[192:193], v[92:93]
	v_lshlrev_b32_e32 v192, 16, v194
	v_and_b32_e32 v193, 0xffff0000, v194
	v_pk_fma_f32 v[94:95], v[10:11], v[192:193], v[94:95]
	s_waitcnt vmcnt(1)
	v_mov_b32_e32 v194, v61
	v_and_b32_e32 v61, 0xffff0000, v60
	v_lshlrev_b32_e32 v60, 16, v60
	v_pk_fma_f32 v[88:89], v[4:5], v[60:61], v[88:89]
	v_lshlrev_b32_e32 v60, 16, v194
	v_and_b32_e32 v61, 0xffff0000, v194
	v_pk_fma_f32 v[90:91], v[6:7], v[60:61], v[90:91]
	s_waitcnt vmcnt(0)
	v_mov_b32_e32 v194, v57
	v_and_b32_e32 v57, 0xffff0000, v56
	v_lshlrev_b32_e32 v56, 16, v56
	v_pk_fma_f32 v[84:85], v[0:1], v[56:57], v[84:85]
	v_lshlrev_b32_e32 v56, 16, v194
	v_and_b32_e32 v57, 0xffff0000, v194
	v_pk_fma_f32 v[86:87], v[2:3], v[56:57], v[86:87]
	s_cmp_lg_u32 s7, 3
	s_cbranch_scc0 .LBB0_1197
